# lorak2: LoRA GEMM per-group trip count (groups 0/1: 2 K-steps, group 2: 4 K-steps)
# baseline (speedup 1.0000x reference)
.LBB0_540:
	s_ashr_i32 s23, s22, 31
	v_cmp_lt_u64_e32 vcc, s[26:27], v[158:159]
	s_lshl_b64 s[26:27], s[22:23], 18
	s_add_u32 s26, s38, s26
	s_addc_u32 s27, s39, s27
	s_lshr_b32 s98, s24, 2
	s_add_i32 s99, s98, 1
	s_mul_i32 s98, s98, s99
	s_lshl_b32 s98, s98, 6
	s_add_u32 s26, s26, s98
	s_addc_u32 s27, s27, 0
	s_and_b64 s[28:29], vcc, exec
	s_cselect_b32 s23, s27, s1
	s_cselect_b32 s61, s26, s0
	s_ashr_i32 s25, s24, 31
	s_lshl_b64 s[28:29], s[24:25], 18
	s_add_u32 s28, s40, s28
	s_addc_u32 s29, s41, s29
	s_add_u32 s28, s28, s98
	s_addc_u32 s29, s29, 0
	s_and_b64 s[34:35], vcc, exec
	s_cselect_b32 s25, s29, s31
	s_cselect_b32 s62, s28, s30
	s_add_u32 s0, s0, 0x20080
	s_addc_u32 s1, s1, 0
	s_add_u32 s63, s30, 0x100
	v_mov_b32_e32 v0, 0
	s_addc_u32 s64, s31, 0
	s_mov_b32 s65, -2
	v_mov_b32_e32 v1, v0
	v_mov_b32_e32 v2, v0
	v_mov_b32_e32 v3, v0
	v_mov_b32_e32 v4, v0
	v_mov_b32_e32 v5, v0
	v_mov_b32_e32 v6, v0
	v_mov_b32_e32 v7, v0
	v_mov_b32_e32 v16, v0
	v_mov_b32_e32 v17, v0
	v_mov_b32_e32 v18, v0
	v_mov_b32_e32 v19, v0
	v_mov_b32_e32 v20, v0
	v_mov_b32_e32 v21, v0
	v_mov_b32_e32 v22, v0
	v_mov_b32_e32 v23, v0
	v_mov_b32_e32 v32, v0
	v_mov_b32_e32 v33, v0
	v_mov_b32_e32 v34, v0
	v_mov_b32_e32 v35, v0
	v_mov_b32_e32 v36, v0
	v_mov_b32_e32 v37, v0
	v_mov_b32_e32 v38, v0
	v_mov_b32_e32 v39, v0
	v_mov_b32_e32 v48, v0
	v_mov_b32_e32 v49, v0
	v_mov_b32_e32 v50, v0
	v_mov_b32_e32 v51, v0
	v_mov_b32_e32 v52, v0
	v_mov_b32_e32 v53, v0
	v_mov_b32_e32 v54, v0
	v_mov_b32_e32 v55, v0
	v_mov_b32_e32 v8, v0
	v_mov_b32_e32 v9, v0
	v_mov_b32_e32 v10, v0
	v_mov_b32_e32 v11, v0
	v_mov_b32_e32 v12, v0
	v_mov_b32_e32 v13, v0
	v_mov_b32_e32 v14, v0
	v_mov_b32_e32 v15, v0
	v_mov_b32_e32 v24, v0
	v_mov_b32_e32 v25, v0
	v_mov_b32_e32 v26, v0
	v_mov_b32_e32 v27, v0
	v_mov_b32_e32 v28, v0
	v_mov_b32_e32 v29, v0
	v_mov_b32_e32 v30, v0
	v_mov_b32_e32 v31, v0
	v_mov_b32_e32 v40, v0
	v_mov_b32_e32 v41, v0
	v_mov_b32_e32 v42, v0
	v_mov_b32_e32 v43, v0
	v_mov_b32_e32 v44, v0
	v_mov_b32_e32 v45, v0
	v_mov_b32_e32 v46, v0
	v_mov_b32_e32 v47, v0
	v_mov_b32_e32 v56, v0
	v_mov_b32_e32 v57, v0
	v_mov_b32_e32 v58, v0
	v_mov_b32_e32 v59, v0
	v_mov_b32_e32 v60, v0
	v_mov_b32_e32 v61, v0
	v_mov_b32_e32 v62, v0
	v_mov_b32_e32 v63, v0
	v_mov_b32_e32 v72, v0
	v_mov_b32_e32 v73, v0
	v_mov_b32_e32 v74, v0
	v_mov_b32_e32 v75, v0
	v_mov_b32_e32 v76, v0
	v_mov_b32_e32 v77, v0
	v_mov_b32_e32 v78, v0
	v_mov_b32_e32 v79, v0
	v_mov_b32_e32 v96, v0
	v_mov_b32_e32 v97, v0
	v_mov_b32_e32 v98, v0
	v_mov_b32_e32 v99, v0
	v_mov_b32_e32 v100, v0
	v_mov_b32_e32 v101, v0
	v_mov_b32_e32 v102, v0
	v_mov_b32_e32 v103, v0
	v_mov_b32_e32 v112, v0
	v_mov_b32_e32 v113, v0
	v_mov_b32_e32 v114, v0
	v_mov_b32_e32 v115, v0
	v_mov_b32_e32 v116, v0
	v_mov_b32_e32 v117, v0
	v_mov_b32_e32 v118, v0
	v_mov_b32_e32 v119, v0
	v_mov_b32_e32 v128, v0
	v_mov_b32_e32 v129, v0
	v_mov_b32_e32 v130, v0
	v_mov_b32_e32 v131, v0
	v_mov_b32_e32 v132, v0
	v_mov_b32_e32 v133, v0
	v_mov_b32_e32 v134, v0
	v_mov_b32_e32 v135, v0
	v_mov_b32_e32 v88, v0
	v_mov_b32_e32 v89, v0
	v_mov_b32_e32 v90, v0
	v_mov_b32_e32 v91, v0
	v_mov_b32_e32 v92, v0
	v_mov_b32_e32 v93, v0
	v_mov_b32_e32 v94, v0
	v_mov_b32_e32 v95, v0
	v_mov_b32_e32 v104, v0
	v_mov_b32_e32 v105, v0
	v_mov_b32_e32 v106, v0
	v_mov_b32_e32 v107, v0
	v_mov_b32_e32 v108, v0
	v_mov_b32_e32 v109, v0
	v_mov_b32_e32 v110, v0
	v_mov_b32_e32 v111, v0
	v_mov_b32_e32 v120, v0
	v_mov_b32_e32 v121, v0
	v_mov_b32_e32 v122, v0
	v_mov_b32_e32 v123, v0
	v_mov_b32_e32 v124, v0
	v_mov_b32_e32 v125, v0
	v_mov_b32_e32 v126, v0
	v_mov_b32_e32 v127, v0
	v_mov_b32_e32 v136, v0
	v_mov_b32_e32 v137, v0
	v_mov_b32_e32 v138, v0
	v_mov_b32_e32 v139, v0
	v_mov_b32_e32 v140, v0
	v_mov_b32_e32 v141, v0
	v_mov_b32_e32 v142, v0
	v_mov_b32_e32 v143, v0
	s_lshr_b32 s100, s33, 2
	s_cmp_eq_u32 s100, 2
	s_cselect_b32 s100, 0, -2
.LBB0_541:
	ds_read_b128 v[64:67], v175
	ds_read_b128 v[68:71], v175 offset:1024
	ds_read_b128 v[80:83], v175 offset:2048
	ds_read_b128 v[84:87], v175 offset:3072
	s_add_u32 s30, s0, 0xfffe0080
	s_addc_u32 s31, s1, -1
	s_cmp_eq_u32 s65, s100
	s_cselect_b32 s35, s23, s31
	s_cselect_b32 s34, s61, s30
	s_cselect_b32 s31, s25, s64
	s_cselect_b32 s30, s62, s63
	v_lshl_add_u64 v[204:205], s[0:1], 0, v[154:155]
	s_add_i32 m0, s43, 0xc000
	ds_read_b128 v[162:165], v176
	ds_read_b128 v[166:169], v176 offset:1024
	ds_read_b128 v[180:183], v176 offset:2048
	ds_read_b128 v[184:187], v176 offset:3072
	ds_read_b128 v[188:191], v176 offset:4096
	ds_read_b128 v[192:195], v176 offset:5120
	ds_read_b128 v[196:199], v176 offset:6144
	ds_read_b128 v[200:203], v176 offset:7168
	global_load_lds_dwordx4 v[204:205], off
	v_lshl_add_u64 v[204:205], s[0:1], 0, v[156:157]
	s_add_i32 m0, s43, 0xe000
	s_nop 0
	global_load_lds_dwordx4 v[204:205], off
	s_waitcnt lgkmcnt(8)
	s_barrier
	s_waitcnt lgkmcnt(0)
	s_setprio 1
	s_waitcnt lgkmcnt(0)
	v_mfma_f32_16x16x32_bf16 v[140:143], v[64:67], v[162:165], v[140:143]
	v_mfma_f32_16x16x32_bf16 v[136:139], v[80:83], v[162:165], v[136:139]
	v_mfma_f32_16x16x32_bf16 v[124:127], v[64:67], v[180:183], v[124:127]
	v_mfma_f32_16x16x32_bf16 v[120:123], v[80:83], v[180:183], v[120:123]
	v_mfma_f32_16x16x32_bf16 v[108:111], v[64:67], v[188:191], v[108:111]
	v_mfma_f32_16x16x32_bf16 v[104:107], v[80:83], v[188:191], v[104:107]
	v_mfma_f32_16x16x32_bf16 v[92:95], v[64:67], v[196:199], v[92:95]
	v_mfma_f32_16x16x32_bf16 v[88:91], v[80:83], v[196:199], v[88:91]
	v_mfma_f32_16x16x32_bf16 v[140:143], v[68:71], v[166:169], v[140:143]
	v_mfma_f32_16x16x32_bf16 v[136:139], v[84:87], v[166:169], v[136:139]
	v_mfma_f32_16x16x32_bf16 v[124:127], v[68:71], v[184:187], v[124:127]
	v_mfma_f32_16x16x32_bf16 v[120:123], v[84:87], v[184:187], v[120:123]
	v_mfma_f32_16x16x32_bf16 v[108:111], v[68:71], v[192:195], v[108:111]
	v_mfma_f32_16x16x32_bf16 v[104:107], v[84:87], v[192:195], v[104:107]
	v_mfma_f32_16x16x32_bf16 v[92:95], v[68:71], v[200:203], v[92:95]
	v_mfma_f32_16x16x32_bf16 v[88:91], v[84:87], v[200:203], v[88:91]
	s_setprio 0
	s_barrier
	s_add_i32 s66, s50, s42
	v_lshl_add_u64 v[220:221], s[30:31], 0, v[148:149]
	s_mov_b32 m0, s66
	ds_read_b128 v[204:207], v177
	ds_read_b128 v[208:211], v177 offset:1024
	ds_read_b128 v[212:215], v177 offset:2048
	ds_read_b128 v[216:219], v177 offset:3072
	global_load_lds_dwordx4 v[220:221], off
	v_lshl_add_u64 v[222:223], s[30:31], 0, v[144:145]
	s_add_i32 m0, s66, 0x2000
	s_nop 0
	global_load_lds_dwordx4 v[222:223], off
	s_barrier
	s_waitcnt lgkmcnt(0)
	s_setprio 1
	s_waitcnt lgkmcnt(0)
	v_mfma_f32_16x16x32_bf16 v[132:135], v[204:207], v[162:165], v[132:135]
	v_mfma_f32_16x16x32_bf16 v[128:131], v[212:215], v[162:165], v[128:131]
	v_mfma_f32_16x16x32_bf16 v[116:119], v[204:207], v[180:183], v[116:119]
	v_mfma_f32_16x16x32_bf16 v[112:115], v[212:215], v[180:183], v[112:115]
	v_mfma_f32_16x16x32_bf16 v[100:103], v[204:207], v[188:191], v[100:103]
	v_mfma_f32_16x16x32_bf16 v[96:99], v[212:215], v[188:191], v[96:99]
	v_mfma_f32_16x16x32_bf16 v[76:79], v[204:207], v[196:199], v[76:79]
	v_mfma_f32_16x16x32_bf16 v[72:75], v[212:215], v[196:199], v[72:75]
	v_mfma_f32_16x16x32_bf16 v[132:135], v[208:211], v[166:169], v[132:135]
	v_mfma_f32_16x16x32_bf16 v[128:131], v[216:219], v[166:169], v[128:131]
	v_mfma_f32_16x16x32_bf16 v[116:119], v[208:211], v[184:187], v[116:119]
	v_mfma_f32_16x16x32_bf16 v[112:115], v[216:219], v[184:187], v[112:115]
	v_mfma_f32_16x16x32_bf16 v[100:103], v[208:211], v[192:195], v[100:103]
	v_mfma_f32_16x16x32_bf16 v[96:99], v[216:219], v[192:195], v[96:99]
	v_mfma_f32_16x16x32_bf16 v[76:79], v[208:211], v[200:203], v[76:79]
	v_mfma_f32_16x16x32_bf16 v[72:75], v[216:219], v[200:203], v[72:75]
	s_setprio 0
	s_mov_b32 m0, s43
	v_lshl_add_u64 v[224:225], s[34:35], 0, v[150:151]
	s_barrier
	ds_read_b128 v[162:165], v176 offset:16384
	ds_read_b128 v[166:169], v176 offset:17408
	ds_read_b128 v[180:183], v176 offset:18432
	ds_read_b128 v[184:187], v176 offset:19456
	ds_read_b128 v[188:191], v176 offset:20480
	ds_read_b128 v[192:195], v176 offset:21504
	ds_read_b128 v[196:199], v176 offset:22528
	ds_read_b128 v[200:203], v176 offset:23552
	global_load_lds_dwordx4 v[224:225], off
	v_lshl_add_u64 v[226:227], s[34:35], 0, v[146:147]
	s_mov_b32 m0, s44
	s_nop 0
	global_load_lds_dwordx4 v[226:227], off
	s_barrier
	s_waitcnt lgkmcnt(0)
	s_setprio 1
	s_waitcnt lgkmcnt(0)
	v_mfma_f32_16x16x32_bf16 v[60:63], v[64:67], v[162:165], v[60:63]
	v_mfma_f32_16x16x32_bf16 v[56:59], v[80:83], v[162:165], v[56:59]
	v_mfma_f32_16x16x32_bf16 v[44:47], v[64:67], v[180:183], v[44:47]
	v_mfma_f32_16x16x32_bf16 v[40:43], v[80:83], v[180:183], v[40:43]
	v_mfma_f32_16x16x32_bf16 v[28:31], v[64:67], v[188:191], v[28:31]
	v_mfma_f32_16x16x32_bf16 v[24:27], v[80:83], v[188:191], v[24:27]
	v_mfma_f32_16x16x32_bf16 v[12:15], v[64:67], v[196:199], v[12:15]
	v_mfma_f32_16x16x32_bf16 v[8:11], v[80:83], v[196:199], v[8:11]
	v_mfma_f32_16x16x32_bf16 v[60:63], v[68:71], v[166:169], v[60:63]
	v_mfma_f32_16x16x32_bf16 v[56:59], v[84:87], v[166:169], v[56:59]
	v_mfma_f32_16x16x32_bf16 v[44:47], v[68:71], v[184:187], v[44:47]
	v_mfma_f32_16x16x32_bf16 v[40:43], v[84:87], v[184:187], v[40:43]
	v_mfma_f32_16x16x32_bf16 v[28:31], v[68:71], v[192:195], v[28:31]
	v_mfma_f32_16x16x32_bf16 v[24:27], v[84:87], v[192:195], v[24:27]
	v_mfma_f32_16x16x32_bf16 v[12:15], v[68:71], v[200:203], v[12:15]
	v_mfma_f32_16x16x32_bf16 v[8:11], v[84:87], v[200:203], v[8:11]
	s_setprio 0
	s_barrier
	s_add_u32 s66, s30, 0x20000
	s_addc_u32 s67, s31, 0
	s_add_i32 s80, s51, s42
	v_lshl_add_u64 v[64:65], s[66:67], 0, v[148:149]
	s_mov_b32 m0, s80
	s_nop 0
	global_load_lds_dwordx4 v[64:65], off
	v_lshl_add_u64 v[64:65], s[66:67], 0, v[144:145]
	s_add_i32 m0, s80, 0x2000
	s_nop 0
	global_load_lds_dwordx4 v[64:65], off
	s_waitcnt vmcnt(6)
	s_barrier
	s_setprio 1
	v_mfma_f32_16x16x32_bf16 v[52:55], v[204:207], v[162:165], v[52:55]
	v_mfma_f32_16x16x32_bf16 v[48:51], v[212:215], v[162:165], v[48:51]
	v_mfma_f32_16x16x32_bf16 v[36:39], v[204:207], v[180:183], v[36:39]
	v_mfma_f32_16x16x32_bf16 v[32:35], v[212:215], v[180:183], v[32:35]
	v_mfma_f32_16x16x32_bf16 v[20:23], v[204:207], v[188:191], v[20:23]
	v_mfma_f32_16x16x32_bf16 v[16:19], v[212:215], v[188:191], v[16:19]
	v_mfma_f32_16x16x32_bf16 v[4:7], v[204:207], v[196:199], v[4:7]
	v_mfma_f32_16x16x32_bf16 v[0:3], v[212:215], v[196:199], v[0:3]
	v_mfma_f32_16x16x32_bf16 v[52:55], v[208:211], v[166:169], v[52:55]
	v_mfma_f32_16x16x32_bf16 v[48:51], v[216:219], v[166:169], v[48:51]
	v_mfma_f32_16x16x32_bf16 v[36:39], v[208:211], v[184:187], v[36:39]
	v_mfma_f32_16x16x32_bf16 v[32:35], v[216:219], v[184:187], v[32:35]
	v_mfma_f32_16x16x32_bf16 v[20:23], v[208:211], v[192:195], v[20:23]
	v_mfma_f32_16x16x32_bf16 v[16:19], v[216:219], v[192:195], v[16:19]
	v_mfma_f32_16x16x32_bf16 v[4:7], v[208:211], v[200:203], v[4:7]
	v_mfma_f32_16x16x32_bf16 v[0:3], v[216:219], v[200:203], v[0:3]
	s_setprio 0
	s_add_i32 s66, 0, 0x18000
	v_add_u32_e32 v84, s66, v173
	s_barrier
	ds_read_b128 v[64:67], v84
	ds_read_b128 v[68:71], v84 offset:1024
	ds_read_b128 v[80:83], v84 offset:2048
	ds_read_b128 v[84:87], v84 offset:3072
	s_add_u32 s34, s34, 0x20000
	s_addc_u32 s35, s35, 0
	s_mov_b32 m0, s45
	v_lshl_add_u64 v[204:205], s[34:35], 0, v[150:151]
	ds_read_b128 v[162:165], v176 offset:32768
	ds_read_b128 v[166:169], v176 offset:33792
	ds_read_b128 v[180:183], v176 offset:34816
	ds_read_b128 v[184:187], v176 offset:35840
	ds_read_b128 v[188:191], v176 offset:36864
	ds_read_b128 v[192:195], v176 offset:37888
	ds_read_b128 v[196:199], v176 offset:38912
	ds_read_b128 v[200:203], v176 offset:39936
	global_load_lds_dwordx4 v[204:205], off
	v_lshl_add_u64 v[204:205], s[34:35], 0, v[146:147]
	s_mov_b32 m0, s46
	s_nop 0
	global_load_lds_dwordx4 v[204:205], off
	s_waitcnt lgkmcnt(8)
	s_barrier
	s_waitcnt lgkmcnt(0)
	s_setprio 1
	s_waitcnt lgkmcnt(0)
	v_mfma_f32_16x16x32_bf16 v[140:143], v[64:67], v[162:165], v[140:143]
	v_mfma_f32_16x16x32_bf16 v[136:139], v[80:83], v[162:165], v[136:139]
	v_mfma_f32_16x16x32_bf16 v[124:127], v[64:67], v[180:183], v[124:127]
	v_mfma_f32_16x16x32_bf16 v[120:123], v[80:83], v[180:183], v[120:123]
	v_mfma_f32_16x16x32_bf16 v[108:111], v[64:67], v[188:191], v[108:111]
	v_mfma_f32_16x16x32_bf16 v[104:107], v[80:83], v[188:191], v[104:107]
	v_mfma_f32_16x16x32_bf16 v[92:95], v[64:67], v[196:199], v[92:95]
	v_mfma_f32_16x16x32_bf16 v[88:91], v[80:83], v[196:199], v[88:91]
	v_mfma_f32_16x16x32_bf16 v[140:143], v[68:71], v[166:169], v[140:143]
	v_mfma_f32_16x16x32_bf16 v[136:139], v[84:87], v[166:169], v[136:139]
	v_mfma_f32_16x16x32_bf16 v[124:127], v[68:71], v[184:187], v[124:127]
	v_mfma_f32_16x16x32_bf16 v[120:123], v[84:87], v[184:187], v[120:123]
	v_mfma_f32_16x16x32_bf16 v[108:111], v[68:71], v[192:195], v[108:111]
	v_mfma_f32_16x16x32_bf16 v[104:107], v[84:87], v[192:195], v[104:107]
	v_mfma_f32_16x16x32_bf16 v[92:95], v[68:71], v[200:203], v[92:95]
	v_mfma_f32_16x16x32_bf16 v[88:91], v[84:87], v[200:203], v[88:91]
	s_setprio 0
	s_barrier
	s_add_i32 s34, 0, 0x1c000
	s_add_i32 s35, s66, s42
	v_add_u32_e32 v152, s34, v173
	v_lshl_add_u64 v[220:221], v[220:221], 0, s[12:13]
	s_mov_b32 m0, s35
	ds_read_b128 v[204:207], v152
	ds_read_b128 v[208:211], v152 offset:1024
	ds_read_b128 v[212:215], v152 offset:2048
	ds_read_b128 v[216:219], v152 offset:3072
	global_load_lds_dwordx4 v[220:221], off
	v_lshl_add_u64 v[220:221], v[222:223], 0, s[12:13]
	s_add_i32 m0, s35, 0x2000
	s_nop 0
	global_load_lds_dwordx4 v[220:221], off
	s_barrier
	s_waitcnt lgkmcnt(0)
	s_setprio 1
	s_waitcnt lgkmcnt(0)
	v_mfma_f32_16x16x32_bf16 v[132:135], v[204:207], v[162:165], v[132:135]
	v_mfma_f32_16x16x32_bf16 v[128:131], v[212:215], v[162:165], v[128:131]
	v_mfma_f32_16x16x32_bf16 v[116:119], v[204:207], v[180:183], v[116:119]
	v_mfma_f32_16x16x32_bf16 v[112:115], v[212:215], v[180:183], v[112:115]
	v_mfma_f32_16x16x32_bf16 v[100:103], v[204:207], v[188:191], v[100:103]
	v_mfma_f32_16x16x32_bf16 v[96:99], v[212:215], v[188:191], v[96:99]
	v_mfma_f32_16x16x32_bf16 v[76:79], v[204:207], v[196:199], v[76:79]
	v_mfma_f32_16x16x32_bf16 v[72:75], v[212:215], v[196:199], v[72:75]
	v_mfma_f32_16x16x32_bf16 v[132:135], v[208:211], v[166:169], v[132:135]
	v_mfma_f32_16x16x32_bf16 v[128:131], v[216:219], v[166:169], v[128:131]
	v_mfma_f32_16x16x32_bf16 v[116:119], v[208:211], v[184:187], v[116:119]
	v_mfma_f32_16x16x32_bf16 v[112:115], v[216:219], v[184:187], v[112:115]
	v_mfma_f32_16x16x32_bf16 v[100:103], v[208:211], v[192:195], v[100:103]
	v_mfma_f32_16x16x32_bf16 v[96:99], v[216:219], v[192:195], v[96:99]
	v_mfma_f32_16x16x32_bf16 v[76:79], v[208:211], v[200:203], v[76:79]
	v_mfma_f32_16x16x32_bf16 v[72:75], v[216:219], v[200:203], v[72:75]
	s_setprio 0
	s_mov_b32 m0, s48
	v_lshl_add_u64 v[220:221], v[224:225], 0, s[12:13]
	s_barrier
	ds_read_b128 v[162:165], v176 offset:49152
	ds_read_b128 v[166:169], v176 offset:50176
	ds_read_b128 v[180:183], v176 offset:51200
	ds_read_b128 v[184:187], v176 offset:52224
	ds_read_b128 v[188:191], v176 offset:53248
	ds_read_b128 v[192:195], v176 offset:54272
	ds_read_b128 v[196:199], v176 offset:55296
	ds_read_b128 v[200:203], v176 offset:56320
	global_load_lds_dwordx4 v[220:221], off
	v_lshl_add_u64 v[220:221], v[226:227], 0, s[12:13]
	s_mov_b32 m0, s49
	s_nop 0
	global_load_lds_dwordx4 v[220:221], off
	s_barrier
	s_waitcnt lgkmcnt(0)
	s_setprio 1
	s_waitcnt lgkmcnt(0)
	v_mfma_f32_16x16x32_bf16 v[60:63], v[64:67], v[162:165], v[60:63]
	v_mfma_f32_16x16x32_bf16 v[56:59], v[80:83], v[162:165], v[56:59]
	v_mfma_f32_16x16x32_bf16 v[44:47], v[64:67], v[180:183], v[44:47]
	v_mfma_f32_16x16x32_bf16 v[40:43], v[80:83], v[180:183], v[40:43]
	v_mfma_f32_16x16x32_bf16 v[28:31], v[64:67], v[188:191], v[28:31]
	v_mfma_f32_16x16x32_bf16 v[24:27], v[80:83], v[188:191], v[24:27]
	v_mfma_f32_16x16x32_bf16 v[12:15], v[64:67], v[196:199], v[12:15]
	v_mfma_f32_16x16x32_bf16 v[8:11], v[80:83], v[196:199], v[8:11]
	v_mfma_f32_16x16x32_bf16 v[60:63], v[68:71], v[166:169], v[60:63]
	v_mfma_f32_16x16x32_bf16 v[56:59], v[84:87], v[166:169], v[56:59]
	v_mfma_f32_16x16x32_bf16 v[44:47], v[68:71], v[184:187], v[44:47]
	v_mfma_f32_16x16x32_bf16 v[40:43], v[84:87], v[184:187], v[40:43]
	v_mfma_f32_16x16x32_bf16 v[28:31], v[68:71], v[192:195], v[28:31]
	v_mfma_f32_16x16x32_bf16 v[24:27], v[84:87], v[192:195], v[24:27]
	v_mfma_f32_16x16x32_bf16 v[12:15], v[68:71], v[200:203], v[12:15]
	v_mfma_f32_16x16x32_bf16 v[8:11], v[84:87], v[200:203], v[8:11]
	s_setprio 0
	s_barrier
	s_add_u32 s30, s30, 0x20080
	s_addc_u32 s31, s31, 0
	s_add_i32 s34, s34, s42
	v_lshl_add_u64 v[64:65], s[30:31], 0, v[148:149]
	s_mov_b32 m0, s34
	s_nop 0
	global_load_lds_dwordx4 v[64:65], off
	v_lshl_add_u64 v[64:65], s[30:31], 0, v[144:145]
	s_add_i32 m0, s34, 0x2000
	s_nop 0
	global_load_lds_dwordx4 v[64:65], off
	s_waitcnt vmcnt(6)
	s_barrier
	s_setprio 1
	v_mfma_f32_16x16x32_bf16 v[52:55], v[204:207], v[162:165], v[52:55]
	v_mfma_f32_16x16x32_bf16 v[48:51], v[212:215], v[162:165], v[48:51]
	v_mfma_f32_16x16x32_bf16 v[36:39], v[204:207], v[180:183], v[36:39]
	v_mfma_f32_16x16x32_bf16 v[32:35], v[212:215], v[180:183], v[32:35]
	v_mfma_f32_16x16x32_bf16 v[20:23], v[204:207], v[188:191], v[20:23]
	v_mfma_f32_16x16x32_bf16 v[16:19], v[212:215], v[188:191], v[16:19]
	v_mfma_f32_16x16x32_bf16 v[4:7], v[204:207], v[196:199], v[4:7]
	v_mfma_f32_16x16x32_bf16 v[0:3], v[212:215], v[196:199], v[0:3]
	v_mfma_f32_16x16x32_bf16 v[52:55], v[208:211], v[166:169], v[52:55]
	v_mfma_f32_16x16x32_bf16 v[48:51], v[216:219], v[166:169], v[48:51]
	v_mfma_f32_16x16x32_bf16 v[36:39], v[208:211], v[184:187], v[36:39]
	v_mfma_f32_16x16x32_bf16 v[32:35], v[216:219], v[184:187], v[32:35]
	v_mfma_f32_16x16x32_bf16 v[20:23], v[208:211], v[192:195], v[20:23]
	v_mfma_f32_16x16x32_bf16 v[16:19], v[216:219], v[192:195], v[16:19]
	v_mfma_f32_16x16x32_bf16 v[4:7], v[208:211], v[200:203], v[4:7]
	v_mfma_f32_16x16x32_bf16 v[0:3], v[216:219], v[200:203], v[0:3]
	s_setprio 0
	s_add_i32 s65, s65, 2
	s_add_u32 s0, s0, 0x100
	s_addc_u32 s1, s1, 0
	s_add_u32 s63, s63, 0x100
	s_addc_u32 s64, s64, 0
	s_cmp_gt_i32 s65, s100
	s_barrier
	s_cbranch_scc0 .LBB0_541
	s_lshl_b32 s0, s33, 8
	s_and_b32 s0, s0, 0x300
	v_readlane_b32 s64, v234, 11
	v_lshl_add_u32 v164, s60, 8, v172
	v_or_b32_e32 v179, s0, v174
	s_cmp_gt_u32 s33, 3
	s_mov_b64 s[0:1], -1
	v_readlane_b32 s65, v234, 12
	v_readlane_b32 s66, v234, 13
	v_readlane_b32 s67, v234, 14
	s_cbranch_scc0 .LBB0_548
	s_cmp_gt_u32 s33, 7
	s_cbranch_scc0 .LBB0_545
	v_lshlrev_b32_e32 v152, 1, v179
	v_ashrrev_i32_e32 v165, 31, v164
	v_lshl_add_u64 v[70:71], s[10:11], 0, v[152:153]
	v_lshlrev_b64 v[64:65], 11, v[164:165]
	v_pk_add_f32 v[68:69], v[142:143], 0 op_sel_hi:[1,0]
	v_pk_add_f32 v[66:67], v[140:141], 0 op_sel_hi:[1,0]
	v_pk_add_f32 v[80:81], v[138:139], 0 op_sel_hi:[1,0]
	v_pk_add_f32 v[82:83], v[136:137], 0 op_sel_hi:[1,0]
	v_lshl_add_u64 v[64:65], v[70:71], 0, v[64:65]
	v_cvt_pk_bf16_f32 v66, v66, v67
	v_cvt_pk_bf16_f32 v67, v68, v69
	v_cvt_pk_bf16_f32 v68, v82, v83
	v_cvt_pk_bf16_f32 v69, v80, v81
	global_store_dwordx4 v[64:65], v[66:69], off
	v_pk_add_f32 v[80:81], v[130:131], 0 op_sel_hi:[1,0]
	v_pk_add_f32 v[82:83], v[128:129], 0 op_sel_hi:[1,0]
	v_pk_add_f32 v[68:69], v[134:135], 0 op_sel_hi:[1,0]
	v_pk_add_f32 v[66:67], v[132:133], 0 op_sel_hi:[1,0]
	v_pk_add_f32 v[84:85], v[120:121], 0 op_sel_hi:[1,0]
	v_cvt_pk_bf16_f32 v66, v66, v67
	v_cvt_pk_bf16_f32 v67, v68, v69
	v_cvt_pk_bf16_f32 v68, v82, v83
	v_cvt_pk_bf16_f32 v69, v80, v81
	global_store_dwordx4 v[64:65], v[66:69], off offset:256
	v_pk_add_f32 v[82:83], v[122:123], 0 op_sel_hi:[1,0]
	v_lshl_add_u64 v[166:167], v[64:65], 0, s[20:21]
	v_or_b32_e32 v66, 16, v164
	v_ashrrev_i32_e32 v67, 31, v66
	v_lshlrev_b64 v[66:67], 11, v[66:67]
	v_lshl_add_u64 v[80:81], v[70:71], 0, v[66:67]
	v_pk_add_f32 v[68:69], v[126:127], 0 op_sel_hi:[1,0]
	v_pk_add_f32 v[66:67], v[124:125], 0 op_sel_hi:[1,0]
	s_mov_b64 s[0:1], 0
	v_cvt_pk_bf16_f32 v66, v66, v67
	v_cvt_pk_bf16_f32 v67, v68, v69
	v_cvt_pk_bf16_f32 v68, v84, v85
	v_cvt_pk_bf16_f32 v69, v82, v83
	global_store_dwordx4 v[80:81], v[66:69], off
	v_pk_add_f32 v[82:83], v[114:115], 0 op_sel_hi:[1,0]
	v_pk_add_f32 v[84:85], v[112:113], 0 op_sel_hi:[1,0]
	v_pk_add_f32 v[68:69], v[118:119], 0 op_sel_hi:[1,0]
	v_pk_add_f32 v[66:67], v[116:117], 0 op_sel_hi:[1,0]
	s_nop 0
	v_cvt_pk_bf16_f32 v66, v66, v67
	v_cvt_pk_bf16_f32 v67, v68, v69
	v_cvt_pk_bf16_f32 v68, v84, v85
	v_cvt_pk_bf16_f32 v69, v82, v83
	global_store_dwordx4 v[80:81], v[66:69], off offset:256
	v_pk_add_f32 v[82:83], v[106:107], 0 op_sel_hi:[1,0]
	v_pk_add_f32 v[84:85], v[104:105], 0 op_sel_hi:[1,0]
	v_or_b32_e32 v66, 32, v164
	v_ashrrev_i32_e32 v67, 31, v66
	v_lshlrev_b64 v[66:67], 11, v[66:67]
	v_lshl_add_u64 v[80:81], v[70:71], 0, v[66:67]
	v_pk_add_f32 v[68:69], v[110:111], 0 op_sel_hi:[1,0]
	v_pk_add_f32 v[66:67], v[108:109], 0 op_sel_hi:[1,0]
	s_nop 0
	v_cvt_pk_bf16_f32 v66, v66, v67
	v_cvt_pk_bf16_f32 v67, v68, v69
	v_cvt_pk_bf16_f32 v68, v84, v85
	v_cvt_pk_bf16_f32 v69, v82, v83
	global_store_dwordx4 v[80:81], v[66:69], off
	v_pk_add_f32 v[82:83], v[98:99], 0 op_sel_hi:[1,0]
	v_pk_add_f32 v[84:85], v[96:97], 0 op_sel_hi:[1,0]
	v_pk_add_f32 v[68:69], v[102:103], 0 op_sel_hi:[1,0]
	v_pk_add_f32 v[66:67], v[100:101], 0 op_sel_hi:[1,0]
	s_nop 0
	v_cvt_pk_bf16_f32 v66, v66, v67
	v_cvt_pk_bf16_f32 v67, v68, v69
	v_cvt_pk_bf16_f32 v68, v84, v85
	v_cvt_pk_bf16_f32 v69, v82, v83
	global_store_dwordx4 v[80:81], v[66:69], off offset:256
	v_pk_add_f32 v[80:81], v[90:91], 0 op_sel_hi:[1,0]
	v_pk_add_f32 v[82:83], v[88:89], 0 op_sel_hi:[1,0]
	v_or_b32_e32 v66, 48, v164
	v_ashrrev_i32_e32 v67, 31, v66
	v_lshlrev_b64 v[66:67], 11, v[66:67]
	v_lshl_add_u64 v[70:71], v[70:71], 0, v[66:67]
	v_pk_add_f32 v[68:69], v[94:95], 0 op_sel_hi:[1,0]
	v_pk_add_f32 v[66:67], v[92:93], 0 op_sel_hi:[1,0]
	s_nop 0
	v_cvt_pk_bf16_f32 v66, v66, v67
	v_cvt_pk_bf16_f32 v67, v68, v69
	v_cvt_pk_bf16_f32 v68, v82, v83
	v_cvt_pk_bf16_f32 v69, v80, v81
	global_store_dwordx4 v[70:71], v[66:69], off
	v_pk_add_f32 v[80:81], v[74:75], 0 op_sel_hi:[1,0]
	v_pk_add_f32 v[82:83], v[72:73], 0 op_sel_hi:[1,0]
	v_pk_add_f32 v[68:69], v[78:79], 0 op_sel_hi:[1,0]
	v_pk_add_f32 v[66:67], v[76:77], 0 op_sel_hi:[1,0]
	s_nop 0
	v_cvt_pk_bf16_f32 v66, v66, v67
	v_cvt_pk_bf16_f32 v67, v68, v69
	v_cvt_pk_bf16_f32 v68, v82, v83
	v_cvt_pk_bf16_f32 v69, v80, v81
	global_store_dwordx4 v[70:71], v[66:69], off offset:256
	v_pk_add_f32 v[80:81], v[58:59], 0 op_sel_hi:[1,0]
	v_pk_add_f32 v[82:83], v[56:57], 0 op_sel_hi:[1,0]
	v_pk_add_f32 v[68:69], v[62:63], 0 op_sel_hi:[1,0]
	v_pk_add_f32 v[66:67], v[60:61], 0 op_sel_hi:[1,0]
	v_lshl_add_u64 v[70:71], v[64:65], 0, s[14:15]
	v_cvt_pk_bf16_f32 v66, v66, v67
	v_cvt_pk_bf16_f32 v67, v68, v69
	v_cvt_pk_bf16_f32 v69, v80, v81
	v_add_co_u32_e32 v80, vcc, s52, v64
	v_cvt_pk_bf16_f32 v68, v82, v83
	s_nop 0
	v_addc_co_u32_e32 v81, vcc, 0, v65, vcc
	global_store_dwordx4 v[80:81], v[66:69], off
	v_pk_add_f32 v[80:81], v[50:51], 0 op_sel_hi:[1,0]
	v_pk_add_f32 v[82:83], v[48:49], 0 op_sel_hi:[1,0]
	v_pk_add_f32 v[68:69], v[54:55], 0 op_sel_hi:[1,0]
	v_pk_add_f32 v[66:67], v[52:53], 0 op_sel_hi:[1,0]
	s_nop 0
	v_cvt_pk_bf16_f32 v66, v66, v67
	v_cvt_pk_bf16_f32 v67, v68, v69
	v_cvt_pk_bf16_f32 v68, v82, v83
	v_cvt_pk_bf16_f32 v69, v80, v81
	global_store_dwordx4 v[70:71], v[66:69], off offset:256
	v_pk_add_f32 v[80:81], v[42:43], 0 op_sel_hi:[1,0]
	v_pk_add_f32 v[82:83], v[40:41], 0 op_sel_hi:[1,0]
	v_pk_add_f32 v[68:69], v[46:47], 0 op_sel_hi:[1,0]
	v_pk_add_f32 v[66:67], v[44:45], 0 op_sel_hi:[1,0]
	v_lshl_add_u64 v[70:71], v[64:65], 0, s[16:17]
	v_cvt_pk_bf16_f32 v66, v66, v67
	v_cvt_pk_bf16_f32 v67, v68, v69
	v_cvt_pk_bf16_f32 v69, v80, v81
	v_add_co_u32_e32 v80, vcc, s53, v64
	v_cvt_pk_bf16_f32 v68, v82, v83
	s_nop 0
	v_addc_co_u32_e32 v81, vcc, 0, v65, vcc
	global_store_dwordx4 v[80:81], v[66:69], off
	v_pk_add_f32 v[80:81], v[34:35], 0 op_sel_hi:[1,0]
	v_pk_add_f32 v[82:83], v[32:33], 0 op_sel_hi:[1,0]
	v_pk_add_f32 v[68:69], v[38:39], 0 op_sel_hi:[1,0]
	v_pk_add_f32 v[66:67], v[36:37], 0 op_sel_hi:[1,0]
	s_nop 0
	v_cvt_pk_bf16_f32 v66, v66, v67
	v_cvt_pk_bf16_f32 v67, v68, v69
	v_cvt_pk_bf16_f32 v68, v82, v83
	v_cvt_pk_bf16_f32 v69, v80, v81
	global_store_dwordx4 v[70:71], v[66:69], off offset:256
	v_pk_add_f32 v[80:81], v[26:27], 0 op_sel_hi:[1,0]
	v_pk_add_f32 v[82:83], v[24:25], 0 op_sel_hi:[1,0]
	v_pk_add_f32 v[68:69], v[30:31], 0 op_sel_hi:[1,0]
	v_pk_add_f32 v[66:67], v[28:29], 0 op_sel_hi:[1,0]
	v_lshl_add_u64 v[70:71], v[64:65], 0, s[18:19]
	v_cvt_pk_bf16_f32 v66, v66, v67
	v_cvt_pk_bf16_f32 v67, v68, v69
	v_cvt_pk_bf16_f32 v69, v80, v81
	v_add_co_u32_e32 v80, vcc, s54, v64
	v_cvt_pk_bf16_f32 v68, v82, v83
	s_nop 0
	v_addc_co_u32_e32 v81, vcc, 0, v65, vcc
	global_store_dwordx4 v[80:81], v[66:69], off
	v_pk_add_f32 v[80:81], v[18:19], 0 op_sel_hi:[1,0]
	v_pk_add_f32 v[82:83], v[16:17], 0 op_sel_hi:[1,0]
	v_pk_add_f32 v[68:69], v[22:23], 0 op_sel_hi:[1,0]
	v_pk_add_f32 v[66:67], v[20:21], 0 op_sel_hi:[1,0]
	v_add_co_u32_e32 v64, vcc, s55, v64
	v_cvt_pk_bf16_f32 v66, v66, v67
	v_cvt_pk_bf16_f32 v67, v68, v69
	v_cvt_pk_bf16_f32 v68, v82, v83
	v_cvt_pk_bf16_f32 v69, v80, v81
	global_store_dwordx4 v[70:71], v[66:69], off offset:256
	v_pk_add_f32 v[70:71], v[10:11], 0 op_sel_hi:[1,0]
	v_pk_add_f32 v[80:81], v[8:9], 0 op_sel_hi:[1,0]
	v_pk_add_f32 v[68:69], v[14:15], 0 op_sel_hi:[1,0]
	v_pk_add_f32 v[66:67], v[12:13], 0 op_sel_hi:[1,0]
	v_addc_co_u32_e32 v65, vcc, 0, v65, vcc
	v_cvt_pk_bf16_f32 v66, v66, v67
	v_cvt_pk_bf16_f32 v67, v68, v69
	v_cvt_pk_bf16_f32 v68, v80, v81
	v_cvt_pk_bf16_f32 v69, v70, v71
	global_store_dwordx4 v[64:65], v[66:69], off
	v_pk_add_f32 v[64:65], v[4:5], 0 op_sel_hi:[1,0]
	v_pk_add_f32 v[70:71], v[0:1], 0 op_sel_hi:[1,0]
	v_pk_add_f32 v[66:67], v[6:7], 0 op_sel_hi:[1,0]
	v_pk_add_f32 v[68:69], v[2:3], 0 op_sel_hi:[1,0]
	v_cvt_pk_bf16_f32 v64, v64, v65
	v_cvt_pk_bf16_f32 v65, v66, v67
	v_cvt_pk_bf16_f32 v66, v70, v71
